# phase2 top-k selection rewritten: bit-sliced radix select in registers, no LDS atomics
# speedup vs baseline: 1.0368x; 1.0368x over previous
; __device__ void phase2(const Params& p, unsigned char* smem) {
;     ...
;     const int nv512 = (nvis + 511) >> 9;
;     {
;       const int tail = nv512 * 512 - nvis;
;       for (int e = tid; e < 8 * tail; e += 512) { int q = e / tail, k = e % tail; sc[q][nvis + k] = 0; }
;     }
;     const u16* QI = (const u16*)(ws + OFF_QI);
;     const float* WI = (const float*)(ws + OFF_WI);
;     const int n16 = lane & 15, g4 = lane >> 4;
;     bf16x8 qa[4][2]; float4 wv[4];
; #pragma unroll
;     for (int pp = 0; pp < 4; pp++) {
;       const int ql = 2 * pp + (n16 >> 3), hh = n16 & 7;
; #pragma unroll
;       for (int kh = 0; kh < 2; kh++)
;         qa[pp][kh] = as_bf8(*(const uint4*)(QI + (size_t)(tok0 + ql) * 512 + hh * 64 + kh * 32 + 8 * g4));
;       wv[pp] = *(const float4*)(WI + (size_t)(tok0 + 2 * pp + (g4 >> 1)) * 8 + 4 * (g4 & 1));
;     }
;     {
;       const int nchunk = nvis >> 6;
;       const u16* kbase = KI + (size_t)n16 * 64 + 8 * g4;
;       bf16x8 nA0, nB0, nA1, nB1, nA2, nB2, nA3, nB3;
;       int c = wave;
;       if (c < nchunk) P2_LOADCHUNK(c, nA0, nB0, nA1, nB1, nA2, nB2, nA3, nB3)
.LBB0_533:
	s_add_i32 s45, s74, 0x1ff
	s_and_b32 s36, s45, 0xfffffe00
	s_sub_i32 s76, s36, s74
	s_lshl_b32 s47, s76, 3
	s_lshr_b32 s73, s45, 9
	v_add_u32_e32 v70, s75, v144
	v_add_u32_e32 v78, s75, v145
	v_ashrrev_i32_e32 v71, 31, v70
	v_ashrrev_i32_e32 v79, 31, v78
	v_lshlrev_b64 v[38:39], 10, v[70:71]
	v_lshlrev_b64 v[46:47], 5, v[78:79]
	v_add_u32_e32 v48, 2, v70
	v_add_u32_e32 v56, 2, v78
	v_add_u32_e32 v62, 4, v70
	v_add_u32_e32 v72, 4, v78
	v_add_u32_e32 v70, 6, v70
	v_add_u32_e32 v78, 6, v78
	v_ashrrev_i32_e32 v49, 31, v48
	v_ashrrev_i32_e32 v57, 31, v56
	v_ashrrev_i32_e32 v63, 31, v62
	v_ashrrev_i32_e32 v73, 31, v72
	v_ashrrev_i32_e32 v71, 31, v70
	v_ashrrev_i32_e32 v79, 31, v78
	v_lshlrev_b64 v[48:49], 10, v[48:49]
	v_lshlrev_b64 v[56:57], 5, v[56:57]
	v_lshlrev_b64 v[62:63], 10, v[62:63]
	v_lshlrev_b64 v[72:73], 5, v[72:73]
	v_lshlrev_b64 v[70:71], 10, v[70:71]
	v_lshlrev_b64 v[78:79], 5, v[78:79]
	v_lshl_add_u64 v[42:43], v[120:121], 0, v[38:39]
	v_lshl_add_u64 v[46:47], v[122:123], 0, v[46:47]
	v_lshl_add_u64 v[54:55], v[120:121], 0, v[48:49]
	v_lshl_add_u64 v[58:59], v[122:123], 0, v[56:57]
	v_lshl_add_u64 v[66:67], v[120:121], 0, v[62:63]
	v_lshl_add_u64 v[72:73], v[122:123], 0, v[72:73]
	v_lshl_add_u64 v[80:81], v[120:121], 0, v[70:71]
	v_lshl_add_u64 v[82:83], v[122:123], 0, v[78:79]
	global_load_dwordx4 v[38:41], v[42:43], off
	s_nop 0
	global_load_dwordx4 v[42:45], v[42:43], off offset:64
	s_nop 0
	global_load_dwordx4 v[46:49], v[46:47], off
	s_nop 0
	global_load_dwordx4 v[50:53], v[54:55], off
	s_nop 0
	global_load_dwordx4 v[54:57], v[54:55], off offset:64
	s_nop 0
	global_load_dwordx4 v[58:61], v[58:59], off
	s_nop 0
	global_load_dwordx4 v[62:65], v[66:67], off
	s_nop 0
	global_load_dwordx4 v[66:69], v[66:67], off offset:64
	s_nop 0
	global_load_dwordx4 v[70:73], v[72:73], off
	s_nop 0
	global_load_dwordx4 v[74:77], v[80:81], off
	s_nop 0
	global_load_dwordx4 v[78:81], v[80:81], off offset:64
	s_nop 0
	global_load_dwordx4 v[82:85], v[82:83], off
	s_lshr_b32 s47, s74, 6
	v_cmp_gt_u32_e64 s[36:37], s47, v133
	s_and_saveexec_b64 s[38:39], s[36:37]
	s_cbranch_execz .LBB0_548
	v_lshl_add_u64 v[6:7], s[48:49], 0, v[118:119]
	v_mov_b32_e32 v139, v119
	v_lshl_add_u64 v[6:7], v[6:7], 0, v[138:139]
	v_mov_b32_e32 v141, v119
	v_lshl_add_u64 v[6:7], v[6:7], 0, v[140:141]
	global_load_dwordx4 v[34:37], v[6:7], off
	global_load_dwordx4 v[30:33], v[6:7], off offset:64
	global_load_dwordx4 v[26:29], v[6:7], off offset:2048
	global_load_dwordx4 v[22:25], v[6:7], off offset:2112
	v_add_co_u32_e32 v6, vcc, 0x1000, v6
	s_nop 1
	v_addc_co_u32_e32 v7, vcc, 0, v7, vcc
	global_load_dwordx4 v[18:21], v[6:7], off
	global_load_dwordx4 v[14:17], v[6:7], off offset:64
	global_load_dwordx4 v[10:13], v[6:7], off offset:2048
	s_nop 0
	global_load_dwordx4 v[6:9], v[6:7], off offset:2112

; __device__ void phase2(const Params& p, unsigned char* smem) {
;     ...
;       const int tail = nv512 * 512 - nvis;
;       for (int e = tid; e < 8 * tail; e += 512) { int q = e / tail, k = e % tail; sc[q][nvis + k] = 0; }
;     ...
;       const u16* my = sc[wave];
;       uint32_t T = 0, need_eq = 0;
;       if (nvis > 256) {
;         uint32_t* hist = (uint32_t*)(smem + 131072) + wave * 256;
;         uint32_t Bsel = 0, above = 0;
; #pragma unroll
;         for (int pass = 0; pass < 2; pass++) {
;           *(uint4*)(hist + lane * 4) = make_uint4(0u, 0u, 0u, 0u);
;           __builtin_amdgcn_fence(__ATOMIC_RELEASE, "wavefront");
;           {
;             uint4 cur = *(const uint4*)(my + lane * 8);
;             for (int j = 0; j < nv512; j++) {
;               uint4 nxt = cur;
;               if (j + 1 < nv512) nxt = *(const uint4*)(my + ((j + 1) * 64 + lane) * 8);
; #pragma unroll
;               for (int e = 0; e < 8; e++) {
;                 const uint32_t w = (e >> 1) == 0 ? cur.x : ((e >> 1) == 1 ? cur.y : ((e >> 1) == 2 ? cur.z : cur.w));
;                 const uint32_t k = (e & 1) ? (w >> 16) : (w & 0xFFFFu);
;                 if (pass == 0) atomicAdd(hist + (k >> 8), 1u);
;                 else if ((k >> 8) == Bsel) atomicAdd(hist + (k & 255u), 1u);
;               }
;               cur = nxt;
;             }
;           }
;           __builtin_amdgcn_fence(__ATOMIC_ACQ_REL, "wavefront");
;           uint4 hh; { const volatile uint32_t* hv_ = hist + lane * 4; hh.x = hv_[0]; hh.y = hv_[1]; hh.z = hv_[2]; hh.w = hv_[3]; }
.LBB0_554:
	s_or_b64 exec, exec, s[38:39]
	s_waitcnt vmcnt(0)
	s_waitcnt lgkmcnt(0)
	s_barrier
	v_mul_u32_u24_e32 v38, s44, v133
	s_lshl_b64 s[36:37], s[58:59], s46
	s_add_u32 s36, s42, s36
	s_addc_u32 s37, s43, s37
	v_lshlrev_b32_e32 v38, 3, v38
	v_mov_b32_e32 v39, v119
	v_lshl_add_u64 v[38:39], s[36:37], 0, v[38:39]
	v_lshl_add_u64 v[46:47], v[136:137], 0, v[38:39]
	v_add_u32_e32 v6, v146, v149
	s_and_b32 s36, s74, 0x1ff
	s_cbranch_scc0 .Lsel_notail
	s_lshr_b32 s36, s36, 3
	s_lshl_b32 s37, s73, 10
	s_addk_i32 s37, 0xfc00
	v_cmp_le_u32_e32 vcc, s36, v154
	v_add_u32_e32 v7, s37, v6
	s_and_saveexec_b64 s[38:39], vcc
	ds_write_b128 v7, v[156:159]
	s_mov_b64 exec, s[38:39]
.Lsel_notail:
	v_mov_b32_e32 v18, 0
	s_mov_b32 s64, 0
	s_cmpk_lt_i32 s74, 0x101
	s_cbranch_scc1 .Lsel_final
	s_mov_b32 s75, 0x0f0f0f0f
	s_mov_b32 s76, 0xf0f0f0f0
	s_mov_b32 s77, 0x33333333
	s_mov_b32 s78, 0xcccccccc
	s_mov_b32 s79, 0x55555555
	s_mov_b32 s80, 0xaaaaaaaa
	s_mov_b32 s81, 0x07030501
	s_mov_b32 s82, 0x06020400
	v_mov_b32_e32 v20, 0
	v_mov_b32_e32 v21, 0
	v_mov_b32_e32 v22, 0
	v_mov_b32_e32 v23, 0
	ds_read_b128 v[168:171], v6 offset:0
	ds_read_b128 v[172:175], v6 offset:1024
	ds_read_b128 v[176:179], v6 offset:2048
	ds_read_b128 v[180:183], v6 offset:3072
	s_cmp_gt_u32 s73, 4
	s_cbranch_scc0 .Lsel_ld_done
	ds_read_b128 v[184:187], v6 offset:4096
	ds_read_b128 v[188:191], v6 offset:5120
	ds_read_b128 v[192:195], v6 offset:6144
	ds_read_b128 v[196:199], v6 offset:7168
	s_cmp_gt_u32 s73, 8
	s_cbranch_scc0 .Lsel_ld_done
	ds_read_b128 v[200:203], v6 offset:8192
	ds_read_b128 v[204:207], v6 offset:9216
	ds_read_b128 v[208:211], v6 offset:10240
	ds_read_b128 v[212:215], v6 offset:11264
	s_cmp_gt_u32 s73, 12
	s_cbranch_scc0 .Lsel_ld_done
	s_waitcnt lgkmcnt(8)
	ds_read_b128 v[216:219], v6 offset:12288
	ds_read_b128 v[220:223], v6 offset:13312
	ds_read_b128 v[224:227], v6 offset:14336
	ds_read_b128 v[228:231], v6 offset:15360
.Lsel_ld_done:
	s_sub_i32 s36, s73, 0
	s_min_u32 s36, s36, 4
	s_mov_b32 s37, 0xffffffff
	s_cmp_eq_u32 s36, 1
	s_cselect_b32 s37, 0xf000f000, s37
	s_cmp_eq_u32 s36, 2
	s_cselect_b32 s37, 0xff00ff00, s37
	s_cmp_eq_u32 s36, 3
	s_cselect_b32 s37, 0xfff0fff0, s37
	v_mov_b32_e32 v20, s37
	s_waitcnt lgkmcnt(0)
	v_perm_b32 v232, v168, v176, s81
	v_perm_b32 v176, v168, v176, s82
	v_perm_b32 v168, v169, v177, s81
	v_perm_b32 v177, v169, v177, s82
	v_perm_b32 v169, v170, v178, s81
	v_perm_b32 v178, v170, v178, s82
	v_perm_b32 v170, v171, v179, s81
	v_perm_b32 v179, v171, v179, s82
	v_perm_b32 v171, v172, v180, s81
	v_perm_b32 v180, v172, v180, s82
	v_perm_b32 v172, v173, v181, s81
	v_perm_b32 v181, v173, v181, s82
	v_perm_b32 v173, v174, v182, s81
	v_perm_b32 v182, v174, v182, s82
	v_perm_b32 v174, v175, v183, s81
	v_perm_b32 v183, v175, v183, s82
	v_lshrrev_b32_e32 v233, 4, v171
	v_lshlrev_b32_e32 v234, 4, v232
	v_bfi_b32 v232, s75, v233, v232
	v_bfi_b32 v171, s76, v234, v171
	v_lshrrev_b32_e32 v233, 4, v172
	v_lshlrev_b32_e32 v234, 4, v168
	v_bfi_b32 v168, s75, v233, v168
	v_bfi_b32 v172, s76, v234, v172
	v_lshrrev_b32_e32 v233, 4, v173
	v_lshlrev_b32_e32 v234, 4, v169
	v_bfi_b32 v169, s75, v233, v169
	v_bfi_b32 v173, s76, v234, v173
	v_lshrrev_b32_e32 v233, 4, v174
	v_lshlrev_b32_e32 v234, 4, v170
	v_bfi_b32 v170, s75, v233, v170
	v_bfi_b32 v174, s76, v234, v174
	v_lshrrev_b32_e32 v233, 4, v180
	v_lshlrev_b32_e32 v234, 4, v176
	v_bfi_b32 v176, s75, v233, v176
	v_bfi_b32 v180, s76, v234, v180
	v_lshrrev_b32_e32 v233, 4, v181
	v_lshlrev_b32_e32 v234, 4, v177
	v_bfi_b32 v177, s75, v233, v177
	v_bfi_b32 v181, s76, v234, v181
	v_lshrrev_b32_e32 v233, 4, v182
	v_lshlrev_b32_e32 v234, 4, v178
	v_bfi_b32 v178, s75, v233, v178
	v_bfi_b32 v182, s76, v234, v182
	v_lshrrev_b32_e32 v233, 4, v183
	v_lshlrev_b32_e32 v234, 4, v179
	v_bfi_b32 v179, s75, v233, v179
	v_bfi_b32 v183, s76, v234, v183
	v_lshrrev_b32_e32 v233, 2, v169
	v_lshlrev_b32_e32 v234, 2, v232
	v_bfi_b32 v232, s77, v233, v232
	v_bfi_b32 v169, s78, v234, v169
	v_lshrrev_b32_e32 v233, 2, v170
	v_lshlrev_b32_e32 v234, 2, v168
	v_bfi_b32 v168, s77, v233, v168
	v_bfi_b32 v170, s78, v234, v170
	v_lshrrev_b32_e32 v233, 2, v173
	v_lshlrev_b32_e32 v234, 2, v171
	v_bfi_b32 v171, s77, v233, v171
	v_bfi_b32 v173, s78, v234, v173
	v_lshrrev_b32_e32 v233, 2, v174
	v_lshlrev_b32_e32 v234, 2, v172
	v_bfi_b32 v172, s77, v233, v172
	v_bfi_b32 v174, s78, v234, v174
	v_lshrrev_b32_e32 v233, 2, v178
	v_lshlrev_b32_e32 v234, 2, v176
	v_bfi_b32 v176, s77, v233, v176
	v_bfi_b32 v178, s78, v234, v178
	v_lshrrev_b32_e32 v233, 2, v179
	v_lshlrev_b32_e32 v234, 2, v177
	v_bfi_b32 v177, s77, v233, v177
	v_bfi_b32 v179, s78, v234, v179
	v_lshrrev_b32_e32 v233, 2, v182
	v_lshlrev_b32_e32 v234, 2, v180
	v_bfi_b32 v180, s77, v233, v180
	v_bfi_b32 v182, s78, v234, v182
	v_lshrrev_b32_e32 v233, 2, v183
	v_lshlrev_b32_e32 v234, 2, v181
	v_bfi_b32 v181, s77, v233, v181
	v_bfi_b32 v183, s78, v234, v183
	v_lshrrev_b32_e32 v233, 1, v168
	v_lshlrev_b32_e32 v234, 1, v232
	v_bfi_b32 v232, s79, v233, v232
	v_bfi_b32 v168, s80, v234, v168
	v_lshrrev_b32_e32 v233, 1, v170
	v_lshlrev_b32_e32 v234, 1, v169
	v_bfi_b32 v169, s79, v233, v169
	v_bfi_b32 v170, s80, v234, v170
	v_lshrrev_b32_e32 v233, 1, v172
	v_lshlrev_b32_e32 v234, 1, v171
	v_bfi_b32 v171, s79, v233, v171
	v_bfi_b32 v172, s80, v234, v172
	v_lshrrev_b32_e32 v233, 1, v174
	v_lshlrev_b32_e32 v234, 1, v173
	v_bfi_b32 v173, s79, v233, v173
	v_bfi_b32 v174, s80, v234, v174
	v_lshrrev_b32_e32 v233, 1, v177
	v_lshlrev_b32_e32 v234, 1, v176
	v_bfi_b32 v176, s79, v233, v176
	v_bfi_b32 v177, s80, v234, v177
	v_lshrrev_b32_e32 v233, 1, v179
	v_lshlrev_b32_e32 v234, 1, v178
	v_bfi_b32 v178, s79, v233, v178
	v_bfi_b32 v179, s80, v234, v179
	v_lshrrev_b32_e32 v233, 1, v181
	v_lshlrev_b32_e32 v234, 1, v180
	v_bfi_b32 v180, s79, v233, v180
	v_bfi_b32 v181, s80, v234, v181
	v_lshrrev_b32_e32 v233, 1, v183
	v_lshlrev_b32_e32 v234, 1, v182
	v_bfi_b32 v182, s79, v233, v182
	v_bfi_b32 v183, s80, v234, v183
	v_mov_b32_e32 v175, v232
	s_cmp_gt_u32 s73, 4
	s_cbranch_scc0 .Lsel_tr_done
; __device__ void phase2(const Params& p, unsigned char* smem) {
;     ...
;         for (int pass = 0; pass < 2; pass++) {
;           *(uint4*)(hist + lane * 4) = make_uint4(0u, 0u, 0u, 0u);
;           __builtin_amdgcn_fence(__ATOMIC_RELEASE, "wavefront");
;           {
;             uint4 cur = *(const uint4*)(my + lane * 8);
;             for (int j = 0; j < nv512; j++) {
;               uint4 nxt = cur;
;               if (j + 1 < nv512) nxt = *(const uint4*)(my + ((j + 1) * 64 + lane) * 8);
; #pragma unroll
;               for (int e = 0; e < 8; e++) {
;                 const uint32_t w = (e >> 1) == 0 ? cur.x : ((e >> 1) == 1 ? cur.y : ((e >> 1) == 2 ? cur.z : cur.w));
;                 const uint32_t k = (e & 1) ? (w >> 16) : (w & 0xFFFFu);
;                 if (pass == 0) atomicAdd(hist + (k >> 8), 1u);
;                 else if ((k >> 8) == Bsel) atomicAdd(hist + (k & 255u), 1u);
;               }
;               cur = nxt;
;             }
;           }
;           __builtin_amdgcn_fence(__ATOMIC_ACQ_REL, "wavefront");
;           uint4 hh; { const volatile uint32_t* hv_ = hist + lane * 4; hh.x = hv_[0]; hh.y = hv_[1]; hh.z = hv_[2]; hh.w = hv_[3]; }
	s_sub_i32 s36, s73, 4
	s_min_u32 s36, s36, 4
	s_mov_b32 s37, 0xffffffff
	s_cmp_eq_u32 s36, 1
	s_cselect_b32 s37, 0xf000f000, s37
	s_cmp_eq_u32 s36, 2
	s_cselect_b32 s37, 0xff00ff00, s37
	s_cmp_eq_u32 s36, 3
	s_cselect_b32 s37, 0xfff0fff0, s37
	v_mov_b32_e32 v21, s37
	v_perm_b32 v232, v184, v192, s81
	v_perm_b32 v192, v184, v192, s82
	v_perm_b32 v184, v185, v193, s81
	v_perm_b32 v193, v185, v193, s82
	v_perm_b32 v185, v186, v194, s81
	v_perm_b32 v194, v186, v194, s82
	v_perm_b32 v186, v187, v195, s81
	v_perm_b32 v195, v187, v195, s82
	v_perm_b32 v187, v188, v196, s81
	v_perm_b32 v196, v188, v196, s82
	v_perm_b32 v188, v189, v197, s81
	v_perm_b32 v197, v189, v197, s82
	v_perm_b32 v189, v190, v198, s81
	v_perm_b32 v198, v190, v198, s82
	v_perm_b32 v190, v191, v199, s81
	v_perm_b32 v199, v191, v199, s82
	v_lshrrev_b32_e32 v233, 4, v187
	v_lshlrev_b32_e32 v234, 4, v232
	v_bfi_b32 v232, s75, v233, v232
	v_bfi_b32 v187, s76, v234, v187
	v_lshrrev_b32_e32 v233, 4, v188
	v_lshlrev_b32_e32 v234, 4, v184
	v_bfi_b32 v184, s75, v233, v184
	v_bfi_b32 v188, s76, v234, v188
	v_lshrrev_b32_e32 v233, 4, v189
	v_lshlrev_b32_e32 v234, 4, v185
	v_bfi_b32 v185, s75, v233, v185
	v_bfi_b32 v189, s76, v234, v189
	v_lshrrev_b32_e32 v233, 4, v190
	v_lshlrev_b32_e32 v234, 4, v186
	v_bfi_b32 v186, s75, v233, v186
	v_bfi_b32 v190, s76, v234, v190
	v_lshrrev_b32_e32 v233, 4, v196
	v_lshlrev_b32_e32 v234, 4, v192
	v_bfi_b32 v192, s75, v233, v192
	v_bfi_b32 v196, s76, v234, v196
	v_lshrrev_b32_e32 v233, 4, v197
	v_lshlrev_b32_e32 v234, 4, v193
	v_bfi_b32 v193, s75, v233, v193
	v_bfi_b32 v197, s76, v234, v197
	v_lshrrev_b32_e32 v233, 4, v198
	v_lshlrev_b32_e32 v234, 4, v194
	v_bfi_b32 v194, s75, v233, v194
	v_bfi_b32 v198, s76, v234, v198
	v_lshrrev_b32_e32 v233, 4, v199
	v_lshlrev_b32_e32 v234, 4, v195
	v_bfi_b32 v195, s75, v233, v195
	v_bfi_b32 v199, s76, v234, v199
	v_lshrrev_b32_e32 v233, 2, v185
	v_lshlrev_b32_e32 v234, 2, v232
	v_bfi_b32 v232, s77, v233, v232
	v_bfi_b32 v185, s78, v234, v185
	v_lshrrev_b32_e32 v233, 2, v186
	v_lshlrev_b32_e32 v234, 2, v184
	v_bfi_b32 v184, s77, v233, v184
	v_bfi_b32 v186, s78, v234, v186
	v_lshrrev_b32_e32 v233, 2, v189
	v_lshlrev_b32_e32 v234, 2, v187
	v_bfi_b32 v187, s77, v233, v187
	v_bfi_b32 v189, s78, v234, v189
	v_lshrrev_b32_e32 v233, 2, v190
	v_lshlrev_b32_e32 v234, 2, v188
	v_bfi_b32 v188, s77, v233, v188
	v_bfi_b32 v190, s78, v234, v190
	v_lshrrev_b32_e32 v233, 2, v194
	v_lshlrev_b32_e32 v234, 2, v192
	v_bfi_b32 v192, s77, v233, v192
	v_bfi_b32 v194, s78, v234, v194
	v_lshrrev_b32_e32 v233, 2, v195
	v_lshlrev_b32_e32 v234, 2, v193
	v_bfi_b32 v193, s77, v233, v193
	v_bfi_b32 v195, s78, v234, v195
	v_lshrrev_b32_e32 v233, 2, v198
	v_lshlrev_b32_e32 v234, 2, v196
	v_bfi_b32 v196, s77, v233, v196
	v_bfi_b32 v198, s78, v234, v198
	v_lshrrev_b32_e32 v233, 2, v199
	v_lshlrev_b32_e32 v234, 2, v197
	v_bfi_b32 v197, s77, v233, v197
	v_bfi_b32 v199, s78, v234, v199
	v_lshrrev_b32_e32 v233, 1, v184
	v_lshlrev_b32_e32 v234, 1, v232
	v_bfi_b32 v232, s79, v233, v232
	v_bfi_b32 v184, s80, v234, v184
	v_lshrrev_b32_e32 v233, 1, v186
	v_lshlrev_b32_e32 v234, 1, v185
	v_bfi_b32 v185, s79, v233, v185
	v_bfi_b32 v186, s80, v234, v186
	v_lshrrev_b32_e32 v233, 1, v188
	v_lshlrev_b32_e32 v234, 1, v187
	v_bfi_b32 v187, s79, v233, v187
	v_bfi_b32 v188, s80, v234, v188
	v_lshrrev_b32_e32 v233, 1, v190
	v_lshlrev_b32_e32 v234, 1, v189
	v_bfi_b32 v189, s79, v233, v189
	v_bfi_b32 v190, s80, v234, v190
	v_lshrrev_b32_e32 v233, 1, v193
	v_lshlrev_b32_e32 v234, 1, v192
	v_bfi_b32 v192, s79, v233, v192
	v_bfi_b32 v193, s80, v234, v193
	v_lshrrev_b32_e32 v233, 1, v195
	v_lshlrev_b32_e32 v234, 1, v194
	v_bfi_b32 v194, s79, v233, v194
	v_bfi_b32 v195, s80, v234, v195
	v_lshrrev_b32_e32 v233, 1, v197
	v_lshlrev_b32_e32 v234, 1, v196
	v_bfi_b32 v196, s79, v233, v196
	v_bfi_b32 v197, s80, v234, v197
	v_lshrrev_b32_e32 v233, 1, v199
	v_lshlrev_b32_e32 v234, 1, v198
	v_bfi_b32 v198, s79, v233, v198
	v_bfi_b32 v199, s80, v234, v199
	v_mov_b32_e32 v191, v232
	s_cmp_gt_u32 s73, 8
	s_cbranch_scc0 .Lsel_tr_done
	s_sub_i32 s36, s73, 8
	s_min_u32 s36, s36, 4
	s_mov_b32 s37, 0xffffffff
	s_cmp_eq_u32 s36, 1
	s_cselect_b32 s37, 0xf000f000, s37
	s_cmp_eq_u32 s36, 2
	s_cselect_b32 s37, 0xff00ff00, s37
	s_cmp_eq_u32 s36, 3
	s_cselect_b32 s37, 0xfff0fff0, s37
	v_mov_b32_e32 v22, s37
	v_perm_b32 v232, v200, v208, s81
	v_perm_b32 v208, v200, v208, s82
	v_perm_b32 v200, v201, v209, s81
	v_perm_b32 v209, v201, v209, s82
	v_perm_b32 v201, v202, v210, s81
	v_perm_b32 v210, v202, v210, s82
	v_perm_b32 v202, v203, v211, s81
	v_perm_b32 v211, v203, v211, s82
	v_perm_b32 v203, v204, v212, s81
	v_perm_b32 v212, v204, v212, s82
	v_perm_b32 v204, v205, v213, s81
	v_perm_b32 v213, v205, v213, s82
	v_perm_b32 v205, v206, v214, s81
	v_perm_b32 v214, v206, v214, s82
	v_perm_b32 v206, v207, v215, s81
	v_perm_b32 v215, v207, v215, s82
	v_lshrrev_b32_e32 v233, 4, v203
	v_lshlrev_b32_e32 v234, 4, v232
	v_bfi_b32 v232, s75, v233, v232
	v_bfi_b32 v203, s76, v234, v203
	v_lshrrev_b32_e32 v233, 4, v204
	v_lshlrev_b32_e32 v234, 4, v200
	v_bfi_b32 v200, s75, v233, v200
	v_bfi_b32 v204, s76, v234, v204
	v_lshrrev_b32_e32 v233, 4, v205
	v_lshlrev_b32_e32 v234, 4, v201
	v_bfi_b32 v201, s75, v233, v201
	v_bfi_b32 v205, s76, v234, v205
	v_lshrrev_b32_e32 v233, 4, v206
	v_lshlrev_b32_e32 v234, 4, v202
	v_bfi_b32 v202, s75, v233, v202
	v_bfi_b32 v206, s76, v234, v206
	v_lshrrev_b32_e32 v233, 4, v212
	v_lshlrev_b32_e32 v234, 4, v208
	v_bfi_b32 v208, s75, v233, v208
	v_bfi_b32 v212, s76, v234, v212
	v_lshrrev_b32_e32 v233, 4, v213
	v_lshlrev_b32_e32 v234, 4, v209
	v_bfi_b32 v209, s75, v233, v209
; __device__ void phase2(const Params& p, unsigned char* smem) {
;     ...
;         for (int pass = 0; pass < 2; pass++) {
;           *(uint4*)(hist + lane * 4) = make_uint4(0u, 0u, 0u, 0u);
;           __builtin_amdgcn_fence(__ATOMIC_RELEASE, "wavefront");
;           {
;             uint4 cur = *(const uint4*)(my + lane * 8);
;             for (int j = 0; j < nv512; j++) {
;               uint4 nxt = cur;
;               if (j + 1 < nv512) nxt = *(const uint4*)(my + ((j + 1) * 64 + lane) * 8);
; #pragma unroll
;               for (int e = 0; e < 8; e++) {
;                 const uint32_t w = (e >> 1) == 0 ? cur.x : ((e >> 1) == 1 ? cur.y : ((e >> 1) == 2 ? cur.z : cur.w));
;                 const uint32_t k = (e & 1) ? (w >> 16) : (w & 0xFFFFu);
;                 if (pass == 0) atomicAdd(hist + (k >> 8), 1u);
;                 else if ((k >> 8) == Bsel) atomicAdd(hist + (k & 255u), 1u);
;               }
;               cur = nxt;
;             }
;           }
;           __builtin_amdgcn_fence(__ATOMIC_ACQ_REL, "wavefront");
;           uint4 hh; { const volatile uint32_t* hv_ = hist + lane * 4; hh.x = hv_[0]; hh.y = hv_[1]; hh.z = hv_[2]; hh.w = hv_[3]; }
	v_bfi_b32 v213, s76, v234, v213
	v_lshrrev_b32_e32 v233, 4, v214
	v_lshlrev_b32_e32 v234, 4, v210
	v_bfi_b32 v210, s75, v233, v210
	v_bfi_b32 v214, s76, v234, v214
	v_lshrrev_b32_e32 v233, 4, v215
	v_lshlrev_b32_e32 v234, 4, v211
	v_bfi_b32 v211, s75, v233, v211
	v_bfi_b32 v215, s76, v234, v215
	v_lshrrev_b32_e32 v233, 2, v201
	v_lshlrev_b32_e32 v234, 2, v232
	v_bfi_b32 v232, s77, v233, v232
	v_bfi_b32 v201, s78, v234, v201
	v_lshrrev_b32_e32 v233, 2, v202
	v_lshlrev_b32_e32 v234, 2, v200
	v_bfi_b32 v200, s77, v233, v200
	v_bfi_b32 v202, s78, v234, v202
	v_lshrrev_b32_e32 v233, 2, v205
	v_lshlrev_b32_e32 v234, 2, v203
	v_bfi_b32 v203, s77, v233, v203
	v_bfi_b32 v205, s78, v234, v205
	v_lshrrev_b32_e32 v233, 2, v206
	v_lshlrev_b32_e32 v234, 2, v204
	v_bfi_b32 v204, s77, v233, v204
	v_bfi_b32 v206, s78, v234, v206
	v_lshrrev_b32_e32 v233, 2, v210
	v_lshlrev_b32_e32 v234, 2, v208
	v_bfi_b32 v208, s77, v233, v208
	v_bfi_b32 v210, s78, v234, v210
	v_lshrrev_b32_e32 v233, 2, v211
	v_lshlrev_b32_e32 v234, 2, v209
	v_bfi_b32 v209, s77, v233, v209
	v_bfi_b32 v211, s78, v234, v211
	v_lshrrev_b32_e32 v233, 2, v214
	v_lshlrev_b32_e32 v234, 2, v212
	v_bfi_b32 v212, s77, v233, v212
	v_bfi_b32 v214, s78, v234, v214
	v_lshrrev_b32_e32 v233, 2, v215
	v_lshlrev_b32_e32 v234, 2, v213
	v_bfi_b32 v213, s77, v233, v213
	v_bfi_b32 v215, s78, v234, v215
	v_lshrrev_b32_e32 v233, 1, v200
	v_lshlrev_b32_e32 v234, 1, v232
	v_bfi_b32 v232, s79, v233, v232
	v_bfi_b32 v200, s80, v234, v200
	v_lshrrev_b32_e32 v233, 1, v202
	v_lshlrev_b32_e32 v234, 1, v201
	v_bfi_b32 v201, s79, v233, v201
	v_bfi_b32 v202, s80, v234, v202
	v_lshrrev_b32_e32 v233, 1, v204
	v_lshlrev_b32_e32 v234, 1, v203
	v_bfi_b32 v203, s79, v233, v203
	v_bfi_b32 v204, s80, v234, v204
	v_lshrrev_b32_e32 v233, 1, v206
	v_lshlrev_b32_e32 v234, 1, v205
	v_bfi_b32 v205, s79, v233, v205
	v_bfi_b32 v206, s80, v234, v206
	v_lshrrev_b32_e32 v233, 1, v209
	v_lshlrev_b32_e32 v234, 1, v208
	v_bfi_b32 v208, s79, v233, v208
	v_bfi_b32 v209, s80, v234, v209
	v_lshrrev_b32_e32 v233, 1, v211
	v_lshlrev_b32_e32 v234, 1, v210
	v_bfi_b32 v210, s79, v233, v210
	v_bfi_b32 v211, s80, v234, v211
	v_lshrrev_b32_e32 v233, 1, v213
	v_lshlrev_b32_e32 v234, 1, v212
	v_bfi_b32 v212, s79, v233, v212
	v_bfi_b32 v213, s80, v234, v213
	v_lshrrev_b32_e32 v233, 1, v215
	v_lshlrev_b32_e32 v234, 1, v214
	v_bfi_b32 v214, s79, v233, v214
	v_bfi_b32 v215, s80, v234, v215
	v_mov_b32_e32 v207, v232
	s_cmp_gt_u32 s73, 12
	s_cbranch_scc0 .Lsel_tr_done
	s_sub_i32 s36, s73, 12
	s_min_u32 s36, s36, 4
	s_mov_b32 s37, 0xffffffff
	s_cmp_eq_u32 s36, 1
	s_cselect_b32 s37, 0xf000f000, s37
	s_cmp_eq_u32 s36, 2
	s_cselect_b32 s37, 0xff00ff00, s37
	s_cmp_eq_u32 s36, 3
	s_cselect_b32 s37, 0xfff0fff0, s37
	v_mov_b32_e32 v23, s37
	v_perm_b32 v232, v216, v224, s81
	v_perm_b32 v224, v216, v224, s82
	v_perm_b32 v216, v217, v225, s81
	v_perm_b32 v225, v217, v225, s82
	v_perm_b32 v217, v218, v226, s81
	v_perm_b32 v226, v218, v226, s82
	v_perm_b32 v218, v219, v227, s81
	v_perm_b32 v227, v219, v227, s82
	v_perm_b32 v219, v220, v228, s81
	v_perm_b32 v228, v220, v228, s82
	v_perm_b32 v220, v221, v229, s81
	v_perm_b32 v229, v221, v229, s82
	v_perm_b32 v221, v222, v230, s81
	v_perm_b32 v230, v222, v230, s82
	v_perm_b32 v222, v223, v231, s81
	v_perm_b32 v231, v223, v231, s82
	v_lshrrev_b32_e32 v233, 4, v219
	v_lshlrev_b32_e32 v234, 4, v232
	v_bfi_b32 v232, s75, v233, v232
	v_bfi_b32 v219, s76, v234, v219
	v_lshrrev_b32_e32 v233, 4, v220
	v_lshlrev_b32_e32 v234, 4, v216
	v_bfi_b32 v216, s75, v233, v216
	v_bfi_b32 v220, s76, v234, v220
	v_lshrrev_b32_e32 v233, 4, v221
	v_lshlrev_b32_e32 v234, 4, v217
	v_bfi_b32 v217, s75, v233, v217
	v_bfi_b32 v221, s76, v234, v221
	v_lshrrev_b32_e32 v233, 4, v222
	v_lshlrev_b32_e32 v234, 4, v218
	v_bfi_b32 v218, s75, v233, v218
	v_bfi_b32 v222, s76, v234, v222
	v_lshrrev_b32_e32 v233, 4, v228
	v_lshlrev_b32_e32 v234, 4, v224
	v_bfi_b32 v224, s75, v233, v224
	v_bfi_b32 v228, s76, v234, v228
	v_lshrrev_b32_e32 v233, 4, v229
	v_lshlrev_b32_e32 v234, 4, v225
	v_bfi_b32 v225, s75, v233, v225
	v_bfi_b32 v229, s76, v234, v229
	v_lshrrev_b32_e32 v233, 4, v230
	v_lshlrev_b32_e32 v234, 4, v226
	v_bfi_b32 v226, s75, v233, v226
	v_bfi_b32 v230, s76, v234, v230
	v_lshrrev_b32_e32 v233, 4, v231
	v_lshlrev_b32_e32 v234, 4, v227
	v_bfi_b32 v227, s75, v233, v227
	v_bfi_b32 v231, s76, v234, v231
	v_lshrrev_b32_e32 v233, 2, v217
	v_lshlrev_b32_e32 v234, 2, v232
	v_bfi_b32 v232, s77, v233, v232
	v_bfi_b32 v217, s78, v234, v217
	v_lshrrev_b32_e32 v233, 2, v218
	v_lshlrev_b32_e32 v234, 2, v216
	v_bfi_b32 v216, s77, v233, v216
	v_bfi_b32 v218, s78, v234, v218
	v_lshrrev_b32_e32 v233, 2, v221
	v_lshlrev_b32_e32 v234, 2, v219
	v_bfi_b32 v219, s77, v233, v219
	v_bfi_b32 v221, s78, v234, v221
	v_lshrrev_b32_e32 v233, 2, v222
	v_lshlrev_b32_e32 v234, 2, v220
	v_bfi_b32 v220, s77, v233, v220
	v_bfi_b32 v222, s78, v234, v222
	v_lshrrev_b32_e32 v233, 2, v226
	v_lshlrev_b32_e32 v234, 2, v224
	v_bfi_b32 v224, s77, v233, v224
	v_bfi_b32 v226, s78, v234, v226
	v_lshrrev_b32_e32 v233, 2, v227
	v_lshlrev_b32_e32 v234, 2, v225
	v_bfi_b32 v225, s77, v233, v225
	v_bfi_b32 v227, s78, v234, v227
	v_lshrrev_b32_e32 v233, 2, v230
	v_lshlrev_b32_e32 v234, 2, v228
	v_bfi_b32 v228, s77, v233, v228
	v_bfi_b32 v230, s78, v234, v230
	v_lshrrev_b32_e32 v233, 2, v231
	v_lshlrev_b32_e32 v234, 2, v229
	v_bfi_b32 v229, s77, v233, v229
	v_bfi_b32 v231, s78, v234, v231
	v_lshrrev_b32_e32 v233, 1, v216
	v_lshlrev_b32_e32 v234, 1, v232
	v_bfi_b32 v232, s79, v233, v232
	v_bfi_b32 v216, s80, v234, v216
	v_lshrrev_b32_e32 v233, 1, v218
	v_lshlrev_b32_e32 v234, 1, v217
	v_bfi_b32 v217, s79, v233, v217
	v_bfi_b32 v218, s80, v234, v218
	v_lshrrev_b32_e32 v233, 1, v220
	v_lshlrev_b32_e32 v234, 1, v219
	v_bfi_b32 v219, s79, v233, v219
	v_bfi_b32 v220, s80, v234, v220
	v_lshrrev_b32_e32 v233, 1, v222
	v_lshlrev_b32_e32 v234, 1, v221
	v_bfi_b32 v221, s79, v233, v221
	v_bfi_b32 v222, s80, v234, v222
	v_lshrrev_b32_e32 v233, 1, v225
	v_lshlrev_b32_e32 v234, 1, v224
	v_bfi_b32 v224, s79, v233, v224
	v_bfi_b32 v225, s80, v234, v225
	v_lshrrev_b32_e32 v233, 1, v227
	v_lshlrev_b32_e32 v234, 1, v226
	v_bfi_b32 v226, s79, v233, v226
	v_bfi_b32 v227, s80, v234, v227
	v_lshrrev_b32_e32 v233, 1, v229
	v_lshlrev_b32_e32 v234, 1, v228
	v_bfi_b32 v228, s79, v233, v228
	v_bfi_b32 v229, s80, v234, v229
	v_lshrrev_b32_e32 v233, 1, v231
	v_lshlrev_b32_e32 v234, 1, v230
	v_bfi_b32 v230, s79, v233, v230
	v_bfi_b32 v231, s80, v234, v231
	v_mov_b32_e32 v223, v232
; __device__ void phase2(const Params& p, unsigned char* smem) {
;     ...
;           const uint32_t target = 256u - above;
;           const uint32_t ssum = hh.x + hh.y + hh.z + hh.w;
;           uint32_t suf = ssum;
; #pragma unroll
;           for (int o = 1; o < 64; o <<= 1) { uint32_t t = __shfl_down(suf, o); if (lane + o < 64) suf += t; }
;           const uint32_t excl = suf - ssum;
;           const bool hit = (excl < target) && (suf >= target);
;           uint32_t bl = 0, ab = 0;
;           {
;             const uint32_t c3 = excl + hh.w, c2 = c3 + hh.z, c1 = c2 + hh.y;
;             if (c3 >= target) { bl = 3; ab = excl; }
;             else if (c2 >= target) { bl = 2; ab = c3; }
;             else if (c1 >= target) { bl = 1; ab = c2; }
;             else { bl = 0; ab = c1; }
;           }
;           const u64 hb = __ballot(hit);
;           const int src = hb ? (int)__builtin_ctzll(hb) : 0;
;           const uint32_t binsel = (uint32_t)__shfl((int)(lane * 4 + bl), src);
;           const uint32_t absel = (uint32_t)__shfl((int)ab, src);
;           if (pass == 0) { Bsel = binsel; above = absel; }
;           else { T = (Bsel << 8) | binsel; need_eq = 256u - (above + absel); }
.Lsel_tr_done:
	s_mov_b32 s62, 0
	s_mov_b32 s63, 0
	v_and_b32_e32 v24, v20, v175
	v_and_b32_e32 v25, v21, v191
	v_and_b32_e32 v26, v22, v207
	v_and_b32_e32 v27, v23, v223
	v_bcnt_u32_b32 v28, v24, 0
	v_bcnt_u32_b32 v29, v25, 0
	v_bcnt_u32_b32 v28, v26, v28
	v_bcnt_u32_b32 v29, v27, v29
	v_add_u32_e32 v28, v28, v29
	s_nop 1
	v_add_u32_dpp v28, v28, v28 quad_perm:[1,0,3,2] row_mask:0xf bank_mask:0xf
	s_nop 1
	v_add_u32_dpp v28, v28, v28 quad_perm:[2,3,0,1] row_mask:0xf bank_mask:0xf
	s_nop 1
	v_add_u32_dpp v28, v28, v28 row_half_mirror row_mask:0xf bank_mask:0xf
	s_nop 1
	v_add_u32_dpp v28, v28, v28 row_mirror row_mask:0xf bank_mask:0xf
	s_nop 0
	v_readlane_b32 s36, v28, 0
	v_readlane_b32 s37, v28, 16
	v_readlane_b32 s38, v28, 32
	v_readlane_b32 s39, v28, 48
	s_add_i32 s36, s36, s37
	s_add_i32 s38, s38, s39
	s_add_i32 s36, s36, s38
	s_add_i32 s36, s36, s62
	s_cmpk_ge_u32 s36, 0x100
	s_cbranch_scc1 .Lsel_r15_one
	s_mov_b32 s62, s36
	v_xor_b32_e32 v20, v20, v24
	v_xor_b32_e32 v21, v21, v25
	v_xor_b32_e32 v22, v22, v26
	v_xor_b32_e32 v23, v23, v27
	s_branch .Lsel_r15_done
.Lsel_r15_one:
	s_bitset1_b32 s63, 15
	v_mov_b32_e32 v20, v24
	v_mov_b32_e32 v21, v25
	v_mov_b32_e32 v22, v26
	v_mov_b32_e32 v23, v27
.Lsel_r15_done:
	v_and_b32_e32 v24, v20, v168
	v_and_b32_e32 v25, v21, v184
	v_and_b32_e32 v26, v22, v200
	v_and_b32_e32 v27, v23, v216
	v_bcnt_u32_b32 v28, v24, 0
	v_bcnt_u32_b32 v29, v25, 0
	v_bcnt_u32_b32 v28, v26, v28
	v_bcnt_u32_b32 v29, v27, v29
	v_add_u32_e32 v28, v28, v29
	s_nop 1
	v_add_u32_dpp v28, v28, v28 quad_perm:[1,0,3,2] row_mask:0xf bank_mask:0xf
	s_nop 1
	v_add_u32_dpp v28, v28, v28 quad_perm:[2,3,0,1] row_mask:0xf bank_mask:0xf
	s_nop 1
	v_add_u32_dpp v28, v28, v28 row_half_mirror row_mask:0xf bank_mask:0xf
	s_nop 1
	v_add_u32_dpp v28, v28, v28 row_mirror row_mask:0xf bank_mask:0xf
	s_nop 0
	v_readlane_b32 s36, v28, 0
	v_readlane_b32 s37, v28, 16
	v_readlane_b32 s38, v28, 32
	v_readlane_b32 s39, v28, 48
	s_add_i32 s36, s36, s37
	s_add_i32 s38, s38, s39
	s_add_i32 s36, s36, s38
	s_add_i32 s36, s36, s62
	s_cmpk_ge_u32 s36, 0x100
	s_cbranch_scc1 .Lsel_r14_one
	s_mov_b32 s62, s36
	v_xor_b32_e32 v20, v20, v24
	v_xor_b32_e32 v21, v21, v25
	v_xor_b32_e32 v22, v22, v26
	v_xor_b32_e32 v23, v23, v27
	s_branch .Lsel_r14_done
.Lsel_r14_one:
	s_bitset1_b32 s63, 14
	v_mov_b32_e32 v20, v24
	v_mov_b32_e32 v21, v25
	v_mov_b32_e32 v22, v26
	v_mov_b32_e32 v23, v27
.Lsel_r14_done:
	v_and_b32_e32 v24, v20, v169
	v_and_b32_e32 v25, v21, v185
	v_and_b32_e32 v26, v22, v201
	v_and_b32_e32 v27, v23, v217
	v_bcnt_u32_b32 v28, v24, 0
	v_bcnt_u32_b32 v29, v25, 0
	v_bcnt_u32_b32 v28, v26, v28
	v_bcnt_u32_b32 v29, v27, v29
	v_add_u32_e32 v28, v28, v29
	s_nop 1
	v_add_u32_dpp v28, v28, v28 quad_perm:[1,0,3,2] row_mask:0xf bank_mask:0xf
	s_nop 1
	v_add_u32_dpp v28, v28, v28 quad_perm:[2,3,0,1] row_mask:0xf bank_mask:0xf
	s_nop 1
	v_add_u32_dpp v28, v28, v28 row_half_mirror row_mask:0xf bank_mask:0xf
	s_nop 1
	v_add_u32_dpp v28, v28, v28 row_mirror row_mask:0xf bank_mask:0xf
	s_nop 0
	v_readlane_b32 s36, v28, 0
	v_readlane_b32 s37, v28, 16
	v_readlane_b32 s38, v28, 32
	v_readlane_b32 s39, v28, 48
	s_add_i32 s36, s36, s37
	s_add_i32 s38, s38, s39
	s_add_i32 s36, s36, s38
	s_add_i32 s36, s36, s62
	s_cmpk_ge_u32 s36, 0x100
	s_cbranch_scc1 .Lsel_r13_one
	s_mov_b32 s62, s36
	v_xor_b32_e32 v20, v20, v24
	v_xor_b32_e32 v21, v21, v25
	v_xor_b32_e32 v22, v22, v26
	v_xor_b32_e32 v23, v23, v27
	s_branch .Lsel_r13_done
.Lsel_r13_one:
	s_bitset1_b32 s63, 13
	v_mov_b32_e32 v20, v24
	v_mov_b32_e32 v21, v25
	v_mov_b32_e32 v22, v26
	v_mov_b32_e32 v23, v27
.Lsel_r13_done:
	v_and_b32_e32 v24, v20, v170
	v_and_b32_e32 v25, v21, v186
	v_and_b32_e32 v26, v22, v202
	v_and_b32_e32 v27, v23, v218
	v_bcnt_u32_b32 v28, v24, 0
	v_bcnt_u32_b32 v29, v25, 0
	v_bcnt_u32_b32 v28, v26, v28
	v_bcnt_u32_b32 v29, v27, v29
	v_add_u32_e32 v28, v28, v29
	s_nop 1
	v_add_u32_dpp v28, v28, v28 quad_perm:[1,0,3,2] row_mask:0xf bank_mask:0xf
	s_nop 1
	v_add_u32_dpp v28, v28, v28 quad_perm:[2,3,0,1] row_mask:0xf bank_mask:0xf
	s_nop 1
	v_add_u32_dpp v28, v28, v28 row_half_mirror row_mask:0xf bank_mask:0xf
	s_nop 1
	v_add_u32_dpp v28, v28, v28 row_mirror row_mask:0xf bank_mask:0xf
	s_nop 0
	v_readlane_b32 s36, v28, 0
	v_readlane_b32 s37, v28, 16
	v_readlane_b32 s38, v28, 32
	v_readlane_b32 s39, v28, 48
	s_add_i32 s36, s36, s37
	s_add_i32 s38, s38, s39
	s_add_i32 s36, s36, s38
	s_add_i32 s36, s36, s62
	s_cmpk_ge_u32 s36, 0x100
	s_cbranch_scc1 .Lsel_r12_one
	s_mov_b32 s62, s36
	v_xor_b32_e32 v20, v20, v24
	v_xor_b32_e32 v21, v21, v25
	v_xor_b32_e32 v22, v22, v26
	v_xor_b32_e32 v23, v23, v27
	s_branch .Lsel_r12_done
.Lsel_r12_one:
	s_bitset1_b32 s63, 12
	v_mov_b32_e32 v20, v24
	v_mov_b32_e32 v21, v25
	v_mov_b32_e32 v22, v26
	v_mov_b32_e32 v23, v27
.Lsel_r12_done:
	v_and_b32_e32 v24, v20, v171
	v_and_b32_e32 v25, v21, v187
	v_and_b32_e32 v26, v22, v203
	v_and_b32_e32 v27, v23, v219
	v_bcnt_u32_b32 v28, v24, 0
	v_bcnt_u32_b32 v29, v25, 0
	v_bcnt_u32_b32 v28, v26, v28
	v_bcnt_u32_b32 v29, v27, v29
	v_add_u32_e32 v28, v28, v29
	s_nop 1
	v_add_u32_dpp v28, v28, v28 quad_perm:[1,0,3,2] row_mask:0xf bank_mask:0xf
	s_nop 1
	v_add_u32_dpp v28, v28, v28 quad_perm:[2,3,0,1] row_mask:0xf bank_mask:0xf
	s_nop 1
	v_add_u32_dpp v28, v28, v28 row_half_mirror row_mask:0xf bank_mask:0xf
	s_nop 1
	v_add_u32_dpp v28, v28, v28 row_mirror row_mask:0xf bank_mask:0xf
	s_nop 0
	v_readlane_b32 s36, v28, 0
	v_readlane_b32 s37, v28, 16
	v_readlane_b32 s38, v28, 32
	v_readlane_b32 s39, v28, 48
	s_add_i32 s36, s36, s37
	s_add_i32 s38, s38, s39
	s_add_i32 s36, s36, s38
	s_add_i32 s36, s36, s62
	s_cmpk_ge_u32 s36, 0x100
	s_cbranch_scc1 .Lsel_r11_one
	s_mov_b32 s62, s36
	v_xor_b32_e32 v20, v20, v24
	v_xor_b32_e32 v21, v21, v25
	v_xor_b32_e32 v22, v22, v26
	v_xor_b32_e32 v23, v23, v27
	s_branch .Lsel_r11_done
; __device__ void phase2(const Params& p, unsigned char* smem) {
;     ...
;           const uint32_t target = 256u - above;
;           const uint32_t ssum = hh.x + hh.y + hh.z + hh.w;
;           uint32_t suf = ssum;
; #pragma unroll
;           for (int o = 1; o < 64; o <<= 1) { uint32_t t = __shfl_down(suf, o); if (lane + o < 64) suf += t; }
;           const uint32_t excl = suf - ssum;
;           const bool hit = (excl < target) && (suf >= target);
;           uint32_t bl = 0, ab = 0;
;           {
;             const uint32_t c3 = excl + hh.w, c2 = c3 + hh.z, c1 = c2 + hh.y;
;             if (c3 >= target) { bl = 3; ab = excl; }
;             else if (c2 >= target) { bl = 2; ab = c3; }
;             else if (c1 >= target) { bl = 1; ab = c2; }
;             else { bl = 0; ab = c1; }
;           }
;           const u64 hb = __ballot(hit);
;           const int src = hb ? (int)__builtin_ctzll(hb) : 0;
;           const uint32_t binsel = (uint32_t)__shfl((int)(lane * 4 + bl), src);
;           const uint32_t absel = (uint32_t)__shfl((int)ab, src);
;           if (pass == 0) { Bsel = binsel; above = absel; }
;           else { T = (Bsel << 8) | binsel; need_eq = 256u - (above + absel); }
.Lsel_r11_one:
	s_bitset1_b32 s63, 11
	v_mov_b32_e32 v20, v24
	v_mov_b32_e32 v21, v25
	v_mov_b32_e32 v22, v26
	v_mov_b32_e32 v23, v27
.Lsel_r11_done:
	v_and_b32_e32 v24, v20, v172
	v_and_b32_e32 v25, v21, v188
	v_and_b32_e32 v26, v22, v204
	v_and_b32_e32 v27, v23, v220
	v_bcnt_u32_b32 v28, v24, 0
	v_bcnt_u32_b32 v29, v25, 0
	v_bcnt_u32_b32 v28, v26, v28
	v_bcnt_u32_b32 v29, v27, v29
	v_add_u32_e32 v28, v28, v29
	s_nop 1
	v_add_u32_dpp v28, v28, v28 quad_perm:[1,0,3,2] row_mask:0xf bank_mask:0xf
	s_nop 1
	v_add_u32_dpp v28, v28, v28 quad_perm:[2,3,0,1] row_mask:0xf bank_mask:0xf
	s_nop 1
	v_add_u32_dpp v28, v28, v28 row_half_mirror row_mask:0xf bank_mask:0xf
	s_nop 1
	v_add_u32_dpp v28, v28, v28 row_mirror row_mask:0xf bank_mask:0xf
	s_nop 0
	v_readlane_b32 s36, v28, 0
	v_readlane_b32 s37, v28, 16
	v_readlane_b32 s38, v28, 32
	v_readlane_b32 s39, v28, 48
	s_add_i32 s36, s36, s37
	s_add_i32 s38, s38, s39
	s_add_i32 s36, s36, s38
	s_add_i32 s36, s36, s62
	s_cmpk_ge_u32 s36, 0x100
	s_cbranch_scc1 .Lsel_r10_one
	s_mov_b32 s62, s36
	v_xor_b32_e32 v20, v20, v24
	v_xor_b32_e32 v21, v21, v25
	v_xor_b32_e32 v22, v22, v26
	v_xor_b32_e32 v23, v23, v27
	s_branch .Lsel_r10_done
.Lsel_r10_one:
	s_bitset1_b32 s63, 10
	v_mov_b32_e32 v20, v24
	v_mov_b32_e32 v21, v25
	v_mov_b32_e32 v22, v26
	v_mov_b32_e32 v23, v27
.Lsel_r10_done:
	v_and_b32_e32 v24, v20, v173
	v_and_b32_e32 v25, v21, v189
	v_and_b32_e32 v26, v22, v205
	v_and_b32_e32 v27, v23, v221
	v_bcnt_u32_b32 v28, v24, 0
	v_bcnt_u32_b32 v29, v25, 0
	v_bcnt_u32_b32 v28, v26, v28
	v_bcnt_u32_b32 v29, v27, v29
	v_add_u32_e32 v28, v28, v29
	s_nop 1
	v_add_u32_dpp v28, v28, v28 quad_perm:[1,0,3,2] row_mask:0xf bank_mask:0xf
	s_nop 1
	v_add_u32_dpp v28, v28, v28 quad_perm:[2,3,0,1] row_mask:0xf bank_mask:0xf
	s_nop 1
	v_add_u32_dpp v28, v28, v28 row_half_mirror row_mask:0xf bank_mask:0xf
	s_nop 1
	v_add_u32_dpp v28, v28, v28 row_mirror row_mask:0xf bank_mask:0xf
	s_nop 0
	v_readlane_b32 s36, v28, 0
	v_readlane_b32 s37, v28, 16
	v_readlane_b32 s38, v28, 32
	v_readlane_b32 s39, v28, 48
	s_add_i32 s36, s36, s37
	s_add_i32 s38, s38, s39
	s_add_i32 s36, s36, s38
	s_add_i32 s36, s36, s62
	s_cmpk_ge_u32 s36, 0x100
	s_cbranch_scc1 .Lsel_r9_one
	s_mov_b32 s62, s36
	v_xor_b32_e32 v20, v20, v24
	v_xor_b32_e32 v21, v21, v25
	v_xor_b32_e32 v22, v22, v26
	v_xor_b32_e32 v23, v23, v27
	s_branch .Lsel_r9_done
.Lsel_r9_one:
	s_bitset1_b32 s63, 9
	v_mov_b32_e32 v20, v24
	v_mov_b32_e32 v21, v25
	v_mov_b32_e32 v22, v26
	v_mov_b32_e32 v23, v27
.Lsel_r9_done:
	v_and_b32_e32 v24, v20, v174
	v_and_b32_e32 v25, v21, v190
	v_and_b32_e32 v26, v22, v206
	v_and_b32_e32 v27, v23, v222
	v_bcnt_u32_b32 v28, v24, 0
	v_bcnt_u32_b32 v29, v25, 0
	v_bcnt_u32_b32 v28, v26, v28
	v_bcnt_u32_b32 v29, v27, v29
	v_add_u32_e32 v28, v28, v29
	s_nop 1
	v_add_u32_dpp v28, v28, v28 quad_perm:[1,0,3,2] row_mask:0xf bank_mask:0xf
	s_nop 1
	v_add_u32_dpp v28, v28, v28 quad_perm:[2,3,0,1] row_mask:0xf bank_mask:0xf
	s_nop 1
	v_add_u32_dpp v28, v28, v28 row_half_mirror row_mask:0xf bank_mask:0xf
	s_nop 1
	v_add_u32_dpp v28, v28, v28 row_mirror row_mask:0xf bank_mask:0xf
	s_nop 0
	v_readlane_b32 s36, v28, 0
	v_readlane_b32 s37, v28, 16
	v_readlane_b32 s38, v28, 32
	v_readlane_b32 s39, v28, 48
	s_add_i32 s36, s36, s37
	s_add_i32 s38, s38, s39
	s_add_i32 s36, s36, s38
	s_add_i32 s36, s36, s62
	s_cmpk_ge_u32 s36, 0x100
	s_cbranch_scc1 .Lsel_r8_one
	s_mov_b32 s62, s36
	v_xor_b32_e32 v20, v20, v24
	v_xor_b32_e32 v21, v21, v25
	v_xor_b32_e32 v22, v22, v26
	v_xor_b32_e32 v23, v23, v27
	s_branch .Lsel_r8_done
.Lsel_r8_one:
	s_bitset1_b32 s63, 8
	v_mov_b32_e32 v20, v24
	v_mov_b32_e32 v21, v25
	v_mov_b32_e32 v22, v26
	v_mov_b32_e32 v23, v27
.Lsel_r8_done:
	v_and_b32_e32 v24, v20, v176
	v_and_b32_e32 v25, v21, v192
	v_and_b32_e32 v26, v22, v208
	v_and_b32_e32 v27, v23, v224
	v_bcnt_u32_b32 v28, v24, 0
	v_bcnt_u32_b32 v29, v25, 0
	v_bcnt_u32_b32 v28, v26, v28
	v_bcnt_u32_b32 v29, v27, v29
	v_add_u32_e32 v28, v28, v29
	s_nop 1
	v_add_u32_dpp v28, v28, v28 quad_perm:[1,0,3,2] row_mask:0xf bank_mask:0xf
	s_nop 1
	v_add_u32_dpp v28, v28, v28 quad_perm:[2,3,0,1] row_mask:0xf bank_mask:0xf
	s_nop 1
	v_add_u32_dpp v28, v28, v28 row_half_mirror row_mask:0xf bank_mask:0xf
	s_nop 1
	v_add_u32_dpp v28, v28, v28 row_mirror row_mask:0xf bank_mask:0xf
	s_nop 0
	v_readlane_b32 s36, v28, 0
	v_readlane_b32 s37, v28, 16
	v_readlane_b32 s38, v28, 32
	v_readlane_b32 s39, v28, 48
	s_add_i32 s36, s36, s37
	s_add_i32 s38, s38, s39
	s_add_i32 s36, s36, s38
	s_add_i32 s36, s36, s62
	s_cmpk_ge_u32 s36, 0x100
	s_cbranch_scc1 .Lsel_r7_one
	s_mov_b32 s62, s36
	v_xor_b32_e32 v20, v20, v24
	v_xor_b32_e32 v21, v21, v25
	v_xor_b32_e32 v22, v22, v26
	v_xor_b32_e32 v23, v23, v27
	s_branch .Lsel_r7_done
.Lsel_r7_one:
	s_bitset1_b32 s63, 7
	v_mov_b32_e32 v20, v24
	v_mov_b32_e32 v21, v25
	v_mov_b32_e32 v22, v26
	v_mov_b32_e32 v23, v27
.Lsel_r7_done:
	v_and_b32_e32 v24, v20, v177
	v_and_b32_e32 v25, v21, v193
	v_and_b32_e32 v26, v22, v209
	v_and_b32_e32 v27, v23, v225
	v_bcnt_u32_b32 v28, v24, 0
	v_bcnt_u32_b32 v29, v25, 0
	v_bcnt_u32_b32 v28, v26, v28
	v_bcnt_u32_b32 v29, v27, v29
	v_add_u32_e32 v28, v28, v29
	s_nop 1
	v_add_u32_dpp v28, v28, v28 quad_perm:[1,0,3,2] row_mask:0xf bank_mask:0xf
	s_nop 1
	v_add_u32_dpp v28, v28, v28 quad_perm:[2,3,0,1] row_mask:0xf bank_mask:0xf
	s_nop 1
	v_add_u32_dpp v28, v28, v28 row_half_mirror row_mask:0xf bank_mask:0xf
	s_nop 1
	v_add_u32_dpp v28, v28, v28 row_mirror row_mask:0xf bank_mask:0xf
	s_nop 0
	v_readlane_b32 s36, v28, 0
	v_readlane_b32 s37, v28, 16
	v_readlane_b32 s38, v28, 32
	v_readlane_b32 s39, v28, 48
	s_add_i32 s36, s36, s37
	s_add_i32 s38, s38, s39
	s_add_i32 s36, s36, s38
	s_add_i32 s36, s36, s62
	s_cmpk_ge_u32 s36, 0x100
	s_cbranch_scc1 .Lsel_r6_one
	s_mov_b32 s62, s36
	v_xor_b32_e32 v20, v20, v24
	v_xor_b32_e32 v21, v21, v25
	v_xor_b32_e32 v22, v22, v26
	v_xor_b32_e32 v23, v23, v27
	s_branch .Lsel_r6_done
; __device__ void phase2(const Params& p, unsigned char* smem) {
;     ...
;           const uint32_t target = 256u - above;
;           const uint32_t ssum = hh.x + hh.y + hh.z + hh.w;
;           uint32_t suf = ssum;
; #pragma unroll
;           for (int o = 1; o < 64; o <<= 1) { uint32_t t = __shfl_down(suf, o); if (lane + o < 64) suf += t; }
;           const uint32_t excl = suf - ssum;
;           const bool hit = (excl < target) && (suf >= target);
;           uint32_t bl = 0, ab = 0;
;           {
;             const uint32_t c3 = excl + hh.w, c2 = c3 + hh.z, c1 = c2 + hh.y;
;             if (c3 >= target) { bl = 3; ab = excl; }
;             else if (c2 >= target) { bl = 2; ab = c3; }
;             else if (c1 >= target) { bl = 1; ab = c2; }
;             else { bl = 0; ab = c1; }
;           }
;           const u64 hb = __ballot(hit);
;           const int src = hb ? (int)__builtin_ctzll(hb) : 0;
;           const uint32_t binsel = (uint32_t)__shfl((int)(lane * 4 + bl), src);
;           const uint32_t absel = (uint32_t)__shfl((int)ab, src);
;           if (pass == 0) { Bsel = binsel; above = absel; }
;           else { T = (Bsel << 8) | binsel; need_eq = 256u - (above + absel); }
.Lsel_r6_one:
	s_bitset1_b32 s63, 6
	v_mov_b32_e32 v20, v24
	v_mov_b32_e32 v21, v25
	v_mov_b32_e32 v22, v26
	v_mov_b32_e32 v23, v27
.Lsel_r6_done:
	v_and_b32_e32 v24, v20, v178
	v_and_b32_e32 v25, v21, v194
	v_and_b32_e32 v26, v22, v210
	v_and_b32_e32 v27, v23, v226
	v_bcnt_u32_b32 v28, v24, 0
	v_bcnt_u32_b32 v29, v25, 0
	v_bcnt_u32_b32 v28, v26, v28
	v_bcnt_u32_b32 v29, v27, v29
	v_add_u32_e32 v28, v28, v29
	s_nop 1
	v_add_u32_dpp v28, v28, v28 quad_perm:[1,0,3,2] row_mask:0xf bank_mask:0xf
	s_nop 1
	v_add_u32_dpp v28, v28, v28 quad_perm:[2,3,0,1] row_mask:0xf bank_mask:0xf
	s_nop 1
	v_add_u32_dpp v28, v28, v28 row_half_mirror row_mask:0xf bank_mask:0xf
	s_nop 1
	v_add_u32_dpp v28, v28, v28 row_mirror row_mask:0xf bank_mask:0xf
	s_nop 0
	v_readlane_b32 s36, v28, 0
	v_readlane_b32 s37, v28, 16
	v_readlane_b32 s38, v28, 32
	v_readlane_b32 s39, v28, 48
	s_add_i32 s36, s36, s37
	s_add_i32 s38, s38, s39
	s_add_i32 s36, s36, s38
	s_add_i32 s36, s36, s62
	s_cmpk_ge_u32 s36, 0x100
	s_cbranch_scc1 .Lsel_r5_one
	s_mov_b32 s62, s36
	v_xor_b32_e32 v20, v20, v24
	v_xor_b32_e32 v21, v21, v25
	v_xor_b32_e32 v22, v22, v26
	v_xor_b32_e32 v23, v23, v27
	s_branch .Lsel_r5_done
.Lsel_r5_one:
	s_bitset1_b32 s63, 5
	v_mov_b32_e32 v20, v24
	v_mov_b32_e32 v21, v25
	v_mov_b32_e32 v22, v26
	v_mov_b32_e32 v23, v27
.Lsel_r5_done:
	v_and_b32_e32 v24, v20, v179
	v_and_b32_e32 v25, v21, v195
	v_and_b32_e32 v26, v22, v211
	v_and_b32_e32 v27, v23, v227
	v_bcnt_u32_b32 v28, v24, 0
	v_bcnt_u32_b32 v29, v25, 0
	v_bcnt_u32_b32 v28, v26, v28
	v_bcnt_u32_b32 v29, v27, v29
	v_add_u32_e32 v28, v28, v29
	s_nop 1
	v_add_u32_dpp v28, v28, v28 quad_perm:[1,0,3,2] row_mask:0xf bank_mask:0xf
	s_nop 1
	v_add_u32_dpp v28, v28, v28 quad_perm:[2,3,0,1] row_mask:0xf bank_mask:0xf
	s_nop 1
	v_add_u32_dpp v28, v28, v28 row_half_mirror row_mask:0xf bank_mask:0xf
	s_nop 1
	v_add_u32_dpp v28, v28, v28 row_mirror row_mask:0xf bank_mask:0xf
	s_nop 0
	v_readlane_b32 s36, v28, 0
	v_readlane_b32 s37, v28, 16
	v_readlane_b32 s38, v28, 32
	v_readlane_b32 s39, v28, 48
	s_add_i32 s36, s36, s37
	s_add_i32 s38, s38, s39
	s_add_i32 s36, s36, s38
	s_add_i32 s36, s36, s62
	s_cmpk_ge_u32 s36, 0x100
	s_cbranch_scc1 .Lsel_r4_one
	s_mov_b32 s62, s36
	v_xor_b32_e32 v20, v20, v24
	v_xor_b32_e32 v21, v21, v25
	v_xor_b32_e32 v22, v22, v26
	v_xor_b32_e32 v23, v23, v27
	s_branch .Lsel_r4_done
.Lsel_r4_one:
	s_bitset1_b32 s63, 4
	v_mov_b32_e32 v20, v24
	v_mov_b32_e32 v21, v25
	v_mov_b32_e32 v22, v26
	v_mov_b32_e32 v23, v27
.Lsel_r4_done:
	v_and_b32_e32 v24, v20, v180
	v_and_b32_e32 v25, v21, v196
	v_and_b32_e32 v26, v22, v212
	v_and_b32_e32 v27, v23, v228
	v_bcnt_u32_b32 v28, v24, 0
	v_bcnt_u32_b32 v29, v25, 0
	v_bcnt_u32_b32 v28, v26, v28
	v_bcnt_u32_b32 v29, v27, v29
	v_add_u32_e32 v28, v28, v29
	s_nop 1
	v_add_u32_dpp v28, v28, v28 quad_perm:[1,0,3,2] row_mask:0xf bank_mask:0xf
	s_nop 1
	v_add_u32_dpp v28, v28, v28 quad_perm:[2,3,0,1] row_mask:0xf bank_mask:0xf
	s_nop 1
	v_add_u32_dpp v28, v28, v28 row_half_mirror row_mask:0xf bank_mask:0xf
	s_nop 1
	v_add_u32_dpp v28, v28, v28 row_mirror row_mask:0xf bank_mask:0xf
	s_nop 0
	v_readlane_b32 s36, v28, 0
	v_readlane_b32 s37, v28, 16
	v_readlane_b32 s38, v28, 32
	v_readlane_b32 s39, v28, 48
	s_add_i32 s36, s36, s37
	s_add_i32 s38, s38, s39
	s_add_i32 s36, s36, s38
	s_add_i32 s36, s36, s62
	s_cmpk_ge_u32 s36, 0x100
	s_cbranch_scc1 .Lsel_r3_one
	s_mov_b32 s62, s36
	v_xor_b32_e32 v20, v20, v24
	v_xor_b32_e32 v21, v21, v25
	v_xor_b32_e32 v22, v22, v26
	v_xor_b32_e32 v23, v23, v27
	s_branch .Lsel_r3_done
.Lsel_r3_one:
	s_bitset1_b32 s63, 3
	v_mov_b32_e32 v20, v24
	v_mov_b32_e32 v21, v25
	v_mov_b32_e32 v22, v26
	v_mov_b32_e32 v23, v27
.Lsel_r3_done:
	v_and_b32_e32 v24, v20, v181
	v_and_b32_e32 v25, v21, v197
	v_and_b32_e32 v26, v22, v213
	v_and_b32_e32 v27, v23, v229
	v_bcnt_u32_b32 v28, v24, 0
	v_bcnt_u32_b32 v29, v25, 0
	v_bcnt_u32_b32 v28, v26, v28
	v_bcnt_u32_b32 v29, v27, v29
	v_add_u32_e32 v28, v28, v29
	s_nop 1
	v_add_u32_dpp v28, v28, v28 quad_perm:[1,0,3,2] row_mask:0xf bank_mask:0xf
	s_nop 1
	v_add_u32_dpp v28, v28, v28 quad_perm:[2,3,0,1] row_mask:0xf bank_mask:0xf
	s_nop 1
	v_add_u32_dpp v28, v28, v28 row_half_mirror row_mask:0xf bank_mask:0xf
	s_nop 1
	v_add_u32_dpp v28, v28, v28 row_mirror row_mask:0xf bank_mask:0xf
	s_nop 0
	v_readlane_b32 s36, v28, 0
	v_readlane_b32 s37, v28, 16
	v_readlane_b32 s38, v28, 32
	v_readlane_b32 s39, v28, 48
	s_add_i32 s36, s36, s37
	s_add_i32 s38, s38, s39
	s_add_i32 s36, s36, s38
	s_add_i32 s36, s36, s62
	s_cmpk_ge_u32 s36, 0x100
	s_cbranch_scc1 .Lsel_r2_one
	s_mov_b32 s62, s36
	v_xor_b32_e32 v20, v20, v24
	v_xor_b32_e32 v21, v21, v25
	v_xor_b32_e32 v22, v22, v26
	v_xor_b32_e32 v23, v23, v27
	s_branch .Lsel_r2_done
.Lsel_r2_one:
	s_bitset1_b32 s63, 2
	v_mov_b32_e32 v20, v24
	v_mov_b32_e32 v21, v25
	v_mov_b32_e32 v22, v26
	v_mov_b32_e32 v23, v27
.Lsel_r2_done:
	v_and_b32_e32 v24, v20, v182
	v_and_b32_e32 v25, v21, v198
	v_and_b32_e32 v26, v22, v214
	v_and_b32_e32 v27, v23, v230
	v_bcnt_u32_b32 v28, v24, 0
	v_bcnt_u32_b32 v29, v25, 0
	v_bcnt_u32_b32 v28, v26, v28
	v_bcnt_u32_b32 v29, v27, v29
	v_add_u32_e32 v28, v28, v29
	s_nop 1
	v_add_u32_dpp v28, v28, v28 quad_perm:[1,0,3,2] row_mask:0xf bank_mask:0xf
	s_nop 1
	v_add_u32_dpp v28, v28, v28 quad_perm:[2,3,0,1] row_mask:0xf bank_mask:0xf
	s_nop 1
	v_add_u32_dpp v28, v28, v28 row_half_mirror row_mask:0xf bank_mask:0xf
	s_nop 1
	v_add_u32_dpp v28, v28, v28 row_mirror row_mask:0xf bank_mask:0xf
	s_nop 0
	v_readlane_b32 s36, v28, 0
	v_readlane_b32 s37, v28, 16
	v_readlane_b32 s38, v28, 32
	v_readlane_b32 s39, v28, 48
	s_add_i32 s36, s36, s37
	s_add_i32 s38, s38, s39
	s_add_i32 s36, s36, s38
	s_add_i32 s36, s36, s62
	s_cmpk_ge_u32 s36, 0x100
	s_cbranch_scc1 .Lsel_r1_one
	s_mov_b32 s62, s36
	v_xor_b32_e32 v20, v20, v24
	v_xor_b32_e32 v21, v21, v25
	v_xor_b32_e32 v22, v22, v26
	v_xor_b32_e32 v23, v23, v27
	s_branch .Lsel_r1_done
; __device__ void phase2(const Params& p, unsigned char* smem) {
;     ...
;       u64* mrow = mrow0 + (size_t)wave * mld;
;       uint32_t eq_seen = 0;
;       const u64 ltmask = (1ull << lane) - 1ull;
;       uint4 cur = *(const uint4*)(my + lane * 8);
;       for (int j = 0; j < nv512; j++) {
;         uint4 nxt = cur;
;         if (j + 1 < nv512) nxt = *(const uint4*)(my + ((j + 1) * 64 + lane) * 8);
;         u64 myword = 0;
; #pragma unroll
;         for (int e = 0; e < 8; e++) {
;           const uint32_t w = (e >> 1) == 0 ? cur.x : ((e >> 1) == 1 ? cur.y : ((e >> 1) == 2 ? cur.z : cur.w));
;           const uint32_t k = (e & 1) ? (w >> 16) : (w & 0xFFFFu);
;           const bool gt = k > T, eq = (k == T);
;           const u64 beq = __ballot(eq);
;           const uint32_t rank = __popcll(beq & ltmask);
;           const bool sel = gt || (eq && (eq_seen + rank) < need_eq);
;           const u64 m = __ballot(sel);
;           eq_seen += __popcll(beq);
;           if (lane == e) myword = m;
;         }
;         if (lane < 8) mrow[j * 8 + lane] = myword;
;         cur = nxt;
;       }
.Lsel_r1_one:
	s_bitset1_b32 s63, 1
	v_mov_b32_e32 v20, v24
	v_mov_b32_e32 v21, v25
	v_mov_b32_e32 v22, v26
	v_mov_b32_e32 v23, v27
.Lsel_r1_done:
	v_and_b32_e32 v24, v20, v183
	v_and_b32_e32 v25, v21, v199
	v_and_b32_e32 v26, v22, v215
	v_and_b32_e32 v27, v23, v231
	v_bcnt_u32_b32 v28, v24, 0
	v_bcnt_u32_b32 v29, v25, 0
	v_bcnt_u32_b32 v28, v26, v28
	v_bcnt_u32_b32 v29, v27, v29
	v_add_u32_e32 v28, v28, v29
	s_nop 1
	v_add_u32_dpp v28, v28, v28 quad_perm:[1,0,3,2] row_mask:0xf bank_mask:0xf
	s_nop 1
	v_add_u32_dpp v28, v28, v28 quad_perm:[2,3,0,1] row_mask:0xf bank_mask:0xf
	s_nop 1
	v_add_u32_dpp v28, v28, v28 row_half_mirror row_mask:0xf bank_mask:0xf
	s_nop 1
	v_add_u32_dpp v28, v28, v28 row_mirror row_mask:0xf bank_mask:0xf
	s_nop 0
	v_readlane_b32 s36, v28, 0
	v_readlane_b32 s37, v28, 16
	v_readlane_b32 s38, v28, 32
	v_readlane_b32 s39, v28, 48
	s_add_i32 s36, s36, s37
	s_add_i32 s38, s38, s39
	s_add_i32 s36, s36, s38
	s_add_i32 s36, s36, s62
	s_cmpk_ge_u32 s36, 0x100
	s_cbranch_scc1 .Lsel_r0_one
	s_mov_b32 s62, s36
	v_xor_b32_e32 v20, v20, v24
	v_xor_b32_e32 v21, v21, v25
	v_xor_b32_e32 v22, v22, v26
	v_xor_b32_e32 v23, v23, v27
	s_branch .Lsel_r0_done
.Lsel_r0_one:
	s_bitset1_b32 s63, 0
	v_mov_b32_e32 v20, v24
	v_mov_b32_e32 v21, v25
	v_mov_b32_e32 v22, v26
	v_mov_b32_e32 v23, v27
.Lsel_r0_done:
	v_mov_b32_e32 v18, s63
	s_sub_i32 s64, 0x100, s62
.Lsel_final:
	ds_read_b128 v[8:11], v6
	s_mov_b32 s65, 0
	s_mov_b32 s66, 0
.Lsel_fl:
	s_add_i32 s66, s66, 1
	v_add_u32_e32 v6, 0x400, v6
	s_waitcnt lgkmcnt(0)
	v_mov_b32_e32 v12, v8
	v_mov_b32_e32 v13, v9
	v_mov_b32_e32 v14, v10
	v_mov_b32_e32 v15, v11
	s_cmp_ge_u32 s66, s73
	s_cbranch_scc1 .Lsel_nold
	ds_read_b128 v[8:11], v6
.Lsel_nold:
	v_cmp_gt_u32_sdwa s[40:41], v12, v18 src0_sel:WORD_0 src1_sel:DWORD
	v_cmp_eq_u32_sdwa s[42:43], v12, v18 src0_sel:WORD_0 src1_sel:DWORD
	s_cmp_lg_u64 s[42:43], 0
	s_cbranch_scc1 .Lsel_tie0
.Lsel_back0:
	v_writelane_b32 v16, s40, 0
	v_writelane_b32 v17, s41, 0
	v_cmp_gt_u32_sdwa s[40:41], v12, v18 src0_sel:WORD_1 src1_sel:DWORD
	v_cmp_eq_u32_sdwa s[42:43], v12, v18 src0_sel:WORD_1 src1_sel:DWORD
	s_cmp_lg_u64 s[42:43], 0
	s_cbranch_scc1 .Lsel_tie1
.Lsel_back1:
	v_writelane_b32 v16, s40, 1
	v_writelane_b32 v17, s41, 1
	v_cmp_gt_u32_sdwa s[40:41], v13, v18 src0_sel:WORD_0 src1_sel:DWORD
	v_cmp_eq_u32_sdwa s[42:43], v13, v18 src0_sel:WORD_0 src1_sel:DWORD
	s_cmp_lg_u64 s[42:43], 0
	s_cbranch_scc1 .Lsel_tie2
.Lsel_back2:
	v_writelane_b32 v16, s40, 2
	v_writelane_b32 v17, s41, 2
	v_cmp_gt_u32_sdwa s[40:41], v13, v18 src0_sel:WORD_1 src1_sel:DWORD
	v_cmp_eq_u32_sdwa s[42:43], v13, v18 src0_sel:WORD_1 src1_sel:DWORD
	s_cmp_lg_u64 s[42:43], 0
	s_cbranch_scc1 .Lsel_tie3
.Lsel_back3:
	v_writelane_b32 v16, s40, 3
	v_writelane_b32 v17, s41, 3
	v_cmp_gt_u32_sdwa s[40:41], v14, v18 src0_sel:WORD_0 src1_sel:DWORD
	v_cmp_eq_u32_sdwa s[42:43], v14, v18 src0_sel:WORD_0 src1_sel:DWORD
	s_cmp_lg_u64 s[42:43], 0
	s_cbranch_scc1 .Lsel_tie4
.Lsel_back4:
	v_writelane_b32 v16, s40, 4
	v_writelane_b32 v17, s41, 4
	v_cmp_gt_u32_sdwa s[40:41], v14, v18 src0_sel:WORD_1 src1_sel:DWORD
	v_cmp_eq_u32_sdwa s[42:43], v14, v18 src0_sel:WORD_1 src1_sel:DWORD
	s_cmp_lg_u64 s[42:43], 0
	s_cbranch_scc1 .Lsel_tie5
.Lsel_back5:
	v_writelane_b32 v16, s40, 5
	v_writelane_b32 v17, s41, 5
	v_cmp_gt_u32_sdwa s[40:41], v15, v18 src0_sel:WORD_0 src1_sel:DWORD
	v_cmp_eq_u32_sdwa s[42:43], v15, v18 src0_sel:WORD_0 src1_sel:DWORD
	s_cmp_lg_u64 s[42:43], 0
	s_cbranch_scc1 .Lsel_tie6
.Lsel_back6:
	v_writelane_b32 v16, s40, 6
	v_writelane_b32 v17, s41, 6
	v_cmp_gt_u32_sdwa s[40:41], v15, v18 src0_sel:WORD_1 src1_sel:DWORD
	v_cmp_eq_u32_sdwa s[42:43], v15, v18 src0_sel:WORD_1 src1_sel:DWORD
	s_cmp_lg_u64 s[42:43], 0
	s_cbranch_scc1 .Lsel_tie7
.Lsel_back7:
	v_writelane_b32 v16, s40, 7
	v_writelane_b32 v17, s41, 7
	s_mov_b64 exec, s[4:5]
	global_store_dwordx2 v[46:47], v[16:17], off
	s_mov_b64 exec, -1
	v_lshl_add_u64 v[46:47], v[46:47], 0, 64
	s_cmp_lt_u32 s66, s73
	s_cbranch_scc1 .Lsel_fl
	s_branch .LBB0_527
.Lsel_tie0:
	s_movk_i32 s67, 0
	s_branch .Lsel_tie
.Lsel_tie1:
	s_movk_i32 s67, 1
	s_branch .Lsel_tie
.Lsel_tie2:
	s_movk_i32 s67, 2
	s_branch .Lsel_tie
.Lsel_tie3:
	s_movk_i32 s67, 3
	s_branch .Lsel_tie
.Lsel_tie4:
	s_movk_i32 s67, 4
	s_branch .Lsel_tie
.Lsel_tie5:
	s_movk_i32 s67, 5
	s_branch .Lsel_tie
.Lsel_tie6:
	s_movk_i32 s67, 6
	s_branch .Lsel_tie
.Lsel_tie7:
	s_movk_i32 s67, 7
	s_branch .Lsel_tie
.Lsel_tie:
	s_sub_i32 s36, s64, s65
	s_bcnt1_i32_b64 s37, s[42:43]
	s_add_i32 s65, s65, s37
.Lsel_tie_loop:
	s_cmp_lt_i32 s36, 1
	s_cbranch_scc1 .Lsel_tie_done
	s_ff1_i32_b64 s37, s[42:43]
	s_cmp_lt_i32 s37, 0
	s_cbranch_scc1 .Lsel_tie_done
	s_bitset1_b64 s[40:41], s37
	s_bitset0_b64 s[42:43], s37
	s_sub_i32 s36, s36, 1
	s_branch .Lsel_tie_loop
.Lsel_tie_done:
	s_cmp_eq_u32 s67, 0
	s_cbranch_scc1 .Lsel_back0
	s_cmp_eq_u32 s67, 1
	s_cbranch_scc1 .Lsel_back1
	s_cmp_eq_u32 s67, 2
	s_cbranch_scc1 .Lsel_back2
	s_cmp_eq_u32 s67, 3
	s_cbranch_scc1 .Lsel_back3
	s_cmp_eq_u32 s67, 4
	s_cbranch_scc1 .Lsel_back4
	s_cmp_eq_u32 s67, 5
	s_cbranch_scc1 .Lsel_back5
	s_cmp_eq_u32 s67, 6
	s_cbranch_scc1 .Lsel_back6
	s_cmp_eq_u32 s67, 7
	s_cbranch_scc1 .Lsel_back7
	s_branch .Lsel_back7
